# v20 with the P3 start stagger halved to one s_sleep 127 (about 3.5us)
# baseline (speedup 1.0000x reference)
; __global__ void __launch_bounds__(NWAVES * 64, 2) fwd_kernel(Args args) {
;     ...
;     xcd_barrier(xbar);
;     ...
;     {
;         pg8::Gemm g{QAB, Wp_t, 1024, 1024, MTOK, 1024, 1024}; pg8::StaticOrder S; S.init(MTOK, 1024, G, bx);
;         pg8::EpiGate E{GT, MG};
;         pg8::gemm_phase<pg8::EpiGate, pg8::StaticOrder, true, true>(ldsp, g, S, E, wave);
.LBB0_613:
	s_waitcnt lgkmcnt(0)
	s_barrier
	s_bfe_u32 s3, s10, 0x10004
	s_cmp_eq_u32 s3, 0
	s_cbranch_scc1 .Lstag_P3_done
.Lstag_P3_loop:
	s_sleep 127
	s_sub_u32 s3, s3, 1
	s_cmp_lg_u32 s3, 0
	s_cbranch_scc1 .Lstag_P3_loop
